# layer-0 mix: blocks < 192 run their context extra item (ctx attention / hyena-ctx / ctx retout) first, then hyena, then attention
# speedup vs baseline: 1.0052x; 1.0052x over previous
.LBB0_615:
	v_readlane_b32 s2, v253, 14
	v_readlane_b32 s4, v252, 50
	s_cmp_lg_u32 s4, 0
	s_cbranch_scc1 .Lg1_std
	s_cmp_eq_u32 s2, 0
	s_cbranch_scc1 .Lg1_x
	s_sub_i32 s2, s2, 1
	s_cmp_gt_u32 s2, 1
	s_cselect_b32 s2, 4, s2
	s_branch .Lg1_std
.Lg1_x:
	s_cmpk_lt_i32 s73, 64
	s_cbranch_scc0 .Lg1_xb
	s_add_i32 s2, s73, 0x200
	s_mov_b32 s3, 1
	s_branch .Lg1_xgo

.Lg1_xnone:
	s_mov_b32 s2, 0
	s_mov_b32 s3, -1
	s_branch .LBB0_25
.Lg1_std:
	s_lshr_b32 s0, s2, 1
	s_mul_i32 s6, s0, s81
	s_add_i32 s6, s6, s73
	s_cmpk_lt_i32 s6, 0x100
	s_cselect_b64 s[0:1], -1, 0
	s_cmpk_gt_i32 s6, 0xff
	s_cbranch_scc1 .LBB0_621
	s_bitcmp0_b32 s2, 0
	s_mov_b64 s[4:5], -1
	s_cbranch_scc1 .LBB0_618
	s_add_i32 s2, s6, 0x100
	s_mov_b64 s[4:5], 0
